# MLA row sum with packed f32 adds (four chains), loop head alignment pinned
# baseline (speedup 1.0000x reference)
.Lmla_norescale_A:
	v_exp_f32_e32 v64, v64
	v_exp_f32_e32 v65, v65
	v_exp_f32_e32 v66, v66
	s_nop 1
	v_exp_f32_e32 v67, v67
	v_exp_f32_e32 v68, v68
	v_exp_f32_e32 v69, v69
	s_nop 1
	v_exp_f32_e32 v70, v70
	v_exp_f32_e32 v71, v71
	v_cvt_pk_bf16_f32 v234, v64, v65
	s_nop 1
	v_cvt_pk_bf16_f32 v235, v66, v67
	v_cvt_pk_bf16_f32 v236, v68, v69
	v_cvt_pk_bf16_f32 v237, v70, v71
	v_exp_f32_e32 v72, v72
	s_nop 1
	v_exp_f32_e32 v73, v73
	v_exp_f32_e32 v74, v74
	v_exp_f32_e32 v75, v75
	s_nop 1
	v_exp_f32_e32 v76, v76
	v_exp_f32_e32 v77, v77
	v_exp_f32_e32 v78, v78
	s_nop 1
	v_exp_f32_e32 v79, v79
	v_cvt_pk_bf16_f32 v238, v72, v73
	v_cvt_pk_bf16_f32 v239, v74, v75
	v_cvt_pk_bf16_f32 v240, v76, v77
	s_nop 1
	v_cvt_pk_bf16_f32 v241, v78, v79
	v_exp_f32_e32 v48, v48
	v_exp_f32_e32 v49, v49
	s_nop 1
	v_exp_f32_e32 v50, v50
	v_exp_f32_e32 v51, v51
	v_exp_f32_e32 v52, v52
	s_nop 1
	v_exp_f32_e32 v53, v53
	v_exp_f32_e32 v54, v54
	v_exp_f32_e32 v55, v55
	s_nop 1
	v_cvt_pk_bf16_f32 v242, v48, v49
	v_cvt_pk_bf16_f32 v243, v50, v51
	v_cvt_pk_bf16_f32 v244, v52, v53
	v_cvt_pk_bf16_f32 v245, v54, v55
	v_exp_f32_e32 v56, v56
	s_nop 1
	v_exp_f32_e32 v57, v57
	v_exp_f32_e32 v58, v58
	v_exp_f32_e32 v59, v59
	s_nop 1
	v_exp_f32_e32 v60, v60
	v_exp_f32_e32 v61, v61
	v_exp_f32_e32 v62, v62
	s_nop 1
	v_exp_f32_e32 v63, v63
	v_cvt_pk_bf16_f32 v246, v56, v57
	v_cvt_pk_bf16_f32 v247, v58, v59
	v_cvt_pk_bf16_f32 v248, v60, v61
	s_nop 1
	v_cvt_pk_bf16_f32 v249, v62, v63
	v_pk_add_f32 v[64:65], v[64:65], v[72:73]
	v_pk_add_f32 v[66:67], v[66:67], v[74:75]
	v_pk_add_f32 v[68:69], v[68:69], v[76:77]
	v_pk_add_f32 v[70:71], v[70:71], v[78:79]
	s_nop 1
	v_pk_add_f32 v[64:65], v[64:65], v[48:49]
	v_pk_add_f32 v[66:67], v[66:67], v[50:51]
	v_pk_add_f32 v[68:69], v[68:69], v[52:53]
	v_pk_add_f32 v[70:71], v[70:71], v[54:55]
	v_pk_add_f32 v[64:65], v[64:65], v[56:57]
	s_nop 1
	v_pk_add_f32 v[66:67], v[66:67], v[58:59]
	v_pk_add_f32 v[68:69], v[68:69], v[60:61]
	v_pk_add_f32 v[70:71], v[70:71], v[62:63]
	v_pk_add_f32 v[64:65], v[64:65], v[66:67]
	v_pk_add_f32 v[68:69], v[68:69], v[70:71]
	s_nop 1
	s_nop 0
	v_pk_add_f32 v[64:65], v[64:65], v[68:69]
	s_nop 0
	v_add_f32_e32 v172, v64, v65
	v_add_f32_e32 v157, v157, v172
	s_mov_b32 s14, 0x41000000
	s_mov_b32 s15, 0
	s_waitcnt lgkmcnt(0)
	s_barrier
	s_add_i32 s28, s28, 1
	s_cmp_lt_i32 s28, s22
	s_cbranch_scc1 .Lmla_A_loop
	v_mfma_f32_32x32x16_bf16 v[16:31], v[202:205], v[234:237], v[16:31]
	v_mfma_f32_32x32x16_bf16 v[0:15], v[218:221], v[234:237], v[0:15]
	v_mfma_f32_32x32x16_bf16 v[16:31], v[206:209], v[238:241], v[16:31]
	v_mfma_f32_32x32x16_bf16 v[0:15], v[222:225], v[238:241], v[0:15]
	v_mfma_f32_32x32x16_bf16 v[16:31], v[210:213], v[242:245], v[16:31]
	v_mfma_f32_32x32x16_bf16 v[0:15], v[226:229], v[242:245], v[0:15]
	v_mfma_f32_32x32x16_bf16 v[16:31], v[214:217], v[246:249], v[16:31]
	v_mfma_f32_32x32x16_bf16 v[0:15], v[230:233], v[246:249], v[0:15]
	s_branch .Lmla_exit

.Lmla_norescale_B:
	v_exp_f32_e32 v64, v64
	v_exp_f32_e32 v65, v65
	v_exp_f32_e32 v66, v66
	v_exp_f32_e32 v67, v67
	v_exp_f32_e32 v68, v68
	v_exp_f32_e32 v69, v69
	v_exp_f32_e32 v70, v70
	v_exp_f32_e32 v71, v71
	v_cvt_pk_bf16_f32 v234, v64, v65
	v_cvt_pk_bf16_f32 v235, v66, v67
	v_cvt_pk_bf16_f32 v236, v68, v69
	v_cvt_pk_bf16_f32 v237, v70, v71
	v_exp_f32_e32 v72, v72
	v_exp_f32_e32 v73, v73
	v_exp_f32_e32 v74, v74
	v_exp_f32_e32 v75, v75
	v_exp_f32_e32 v76, v76
	v_exp_f32_e32 v77, v77
	v_exp_f32_e32 v78, v78
	v_exp_f32_e32 v79, v79
	v_cvt_pk_bf16_f32 v238, v72, v73
	v_cvt_pk_bf16_f32 v239, v74, v75
	v_cvt_pk_bf16_f32 v240, v76, v77
	v_cvt_pk_bf16_f32 v241, v78, v79
	v_exp_f32_e32 v48, v48
	v_exp_f32_e32 v49, v49
	v_exp_f32_e32 v50, v50
	v_exp_f32_e32 v51, v51
	v_exp_f32_e32 v52, v52
	v_exp_f32_e32 v53, v53
	v_exp_f32_e32 v54, v54
	v_exp_f32_e32 v55, v55
	v_cvt_pk_bf16_f32 v242, v48, v49
	v_cvt_pk_bf16_f32 v243, v50, v51
	v_cvt_pk_bf16_f32 v244, v52, v53
	v_cvt_pk_bf16_f32 v245, v54, v55
	v_exp_f32_e32 v56, v56
	v_exp_f32_e32 v57, v57
	v_exp_f32_e32 v58, v58
	v_exp_f32_e32 v59, v59
	v_exp_f32_e32 v60, v60
	v_exp_f32_e32 v61, v61
	v_exp_f32_e32 v62, v62
	v_exp_f32_e32 v63, v63
	v_cvt_pk_bf16_f32 v246, v56, v57
	v_cvt_pk_bf16_f32 v247, v58, v59
	v_cvt_pk_bf16_f32 v248, v60, v61
	v_cvt_pk_bf16_f32 v249, v62, v63
	v_pk_add_f32 v[64:65], v[64:65], v[72:73]
	v_pk_add_f32 v[66:67], v[66:67], v[74:75]
	v_pk_add_f32 v[68:69], v[68:69], v[76:77]
	v_pk_add_f32 v[70:71], v[70:71], v[78:79]
	v_pk_add_f32 v[64:65], v[64:65], v[48:49]
	v_pk_add_f32 v[66:67], v[66:67], v[50:51]
	v_pk_add_f32 v[68:69], v[68:69], v[52:53]
	v_pk_add_f32 v[70:71], v[70:71], v[54:55]
	v_pk_add_f32 v[64:65], v[64:65], v[56:57]
	v_pk_add_f32 v[66:67], v[66:67], v[58:59]
	v_pk_add_f32 v[68:69], v[68:69], v[60:61]
	v_pk_add_f32 v[70:71], v[70:71], v[62:63]
	v_pk_add_f32 v[64:65], v[64:65], v[66:67]
	v_pk_add_f32 v[68:69], v[68:69], v[70:71]
	s_nop 0
	v_pk_add_f32 v[64:65], v[64:65], v[68:69]
	s_nop 0
	v_add_f32_e32 v172, v64, v65
	v_add_f32_e32 v157, v157, v172
	s_mov_b32 s14, 0x41000000
	s_mov_b32 s15, 0
	s_and_b32 s12, s28, 1
	s_mul_i32 s13, s12, 0x3400
	v_add_u32_e32 v52, s13, v112
	ds_read_b128 v[48:51], v52
	ds_read_b128 v[122:125], v52 offset:6656
	ds_read_b128 v[118:121], v52 offset:32
	ds_read_b128 v[126:129], v52 offset:6688
	ds_read_b128 v[130:133], v52 offset:64
	ds_read_b128 v[138:141], v52 offset:6720
	ds_read_b128 v[134:137], v52 offset:96
	ds_read_b128 v[142:145], v52 offset:6752
	ds_read_b128 v[146:149], v52 offset:128
	ds_read_b128 v[194:197], v52 offset:6784
	ds_read_b128 v[178:181], v52 offset:160
	ds_read_b128 v[198:201], v52 offset:6816
	s_mul_i32 s13, s12, 0x2400
	v_add_u32_e32 v177, s13, v176
	s_setprio 3
	v_mfma_f32_32x32x16_bf16 v[16:31], v[202:205], v[234:237], v[16:31]
	v_mfma_f32_32x32x16_bf16 v[0:15], v[218:221], v[234:237], v[0:15]
	v_mfma_f32_32x32x16_bf16 v[16:31], v[206:209], v[238:241], v[16:31]
	v_mfma_f32_32x32x16_bf16 v[0:15], v[222:225], v[238:241], v[0:15]
	v_mfma_f32_32x32x16_bf16 v[16:31], v[210:213], v[242:245], v[16:31]
	v_mfma_f32_32x32x16_bf16 v[0:15], v[226:229], v[242:245], v[0:15]
	v_mfma_f32_32x32x16_bf16 v[16:31], v[214:217], v[246:249], v[16:31]
	v_mfma_f32_32x32x16_bf16 v[0:15], v[230:233], v[246:249], v[0:15]
	s_waitcnt lgkmcnt(11)
	v_mfma_f32_32x32x16_bf16 v[64:79], v[48:51], v[80:83], v[32:47]
	s_waitcnt lgkmcnt(10)
	v_mfma_f32_32x32x16_bf16 v[48:63], v[122:125], v[80:83], v[32:47]
	s_waitcnt lgkmcnt(9)
	v_mfma_f32_32x32x16_bf16 v[64:79], v[118:121], v[84:87], v[64:79]
	s_waitcnt lgkmcnt(8)
	v_mfma_f32_32x32x16_bf16 v[48:63], v[126:129], v[84:87], v[48:63]
	s_waitcnt lgkmcnt(7)
	v_mfma_f32_32x32x16_bf16 v[64:79], v[130:133], v[88:91], v[64:79]
	s_waitcnt lgkmcnt(6)
	v_mfma_f32_32x32x16_bf16 v[48:63], v[138:141], v[88:91], v[48:63]
	s_waitcnt lgkmcnt(5)
	v_mfma_f32_32x32x16_bf16 v[64:79], v[134:137], v[92:95], v[64:79]
	s_waitcnt lgkmcnt(4)
	v_mfma_f32_32x32x16_bf16 v[48:63], v[142:145], v[92:95], v[48:63]
	s_waitcnt lgkmcnt(3)
	v_mfma_f32_32x32x16_bf16 v[64:79], v[146:149], v[96:99], v[64:79]
	ds_read_b128 v[202:205], v177 offset:26624
	ds_read_b128 v[206:209], v177 offset:26656
	ds_read_b128 v[218:221], v177 offset:31232
	ds_read_b128 v[222:225], v177 offset:31264
	ds_read_b128 v[210:213], v177 offset:26688
	ds_read_b128 v[214:217], v177 offset:26720
	ds_read_b128 v[226:229], v177 offset:31296
	ds_read_b128 v[230:233], v177 offset:31328
	s_waitcnt lgkmcnt(10)
	v_mfma_f32_32x32x16_bf16 v[48:63], v[194:197], v[96:99], v[48:63]
	s_add_i32 s12, s28, 1
	s_cmp_ge_i32 s12, s22
	s_cbranch_scc1 .Lmla_nowrite_B
	s_and_b32 s12, s12, 1
	s_mul_i32 s13, s12, 0x3400
	v_add3_u32 v172, s13, v165, v166
	s_waitcnt vmcnt(0)
	ds_write_b128 v172, v[104:107]
	s_mulk_i32 s12, 0x2400
	v_add_u32_e32 v172, s12, v169
	v_add_u32_e32 v172, 0x6800, v172
	ds_write2_b64 v172, v[114:115], v[116:117] offset1:2
	s_add_i32 s12, s28, 2
	s_cmp_ge_i32 s12, s22
	s_cbranch_scc1 .Lmla_nowrite_B
	s_nop 1
	global_load_dwordx4 v[104:107], v[150:151], off
	global_load_dwordx4 v[114:117], v[152:153], off
	v_lshl_add_u64 v[150:151], v[150:151], 0, s[26:27]
	v_lshl_add_u64 v[152:153], v[152:153], 0, s[30:31]

.Lmla_norescale_Bt:
	v_exp_f32_e32 v64, v64
	v_exp_f32_e32 v65, v65
	v_exp_f32_e32 v66, v66
	v_exp_f32_e32 v67, v67
	v_exp_f32_e32 v68, v68
	v_exp_f32_e32 v69, v69
	v_exp_f32_e32 v70, v70
	v_exp_f32_e32 v71, v71
	v_cvt_pk_bf16_f32 v234, v64, v65
	v_cvt_pk_bf16_f32 v235, v66, v67
	v_cvt_pk_bf16_f32 v236, v68, v69
	v_cvt_pk_bf16_f32 v237, v70, v71
	v_exp_f32_e32 v72, v72
	v_exp_f32_e32 v73, v73
	v_exp_f32_e32 v74, v74
	v_exp_f32_e32 v75, v75
	v_exp_f32_e32 v76, v76
	v_exp_f32_e32 v77, v77
	v_exp_f32_e32 v78, v78
	v_exp_f32_e32 v79, v79
	v_cvt_pk_bf16_f32 v238, v72, v73
	v_cvt_pk_bf16_f32 v239, v74, v75
	v_cvt_pk_bf16_f32 v240, v76, v77
	v_cvt_pk_bf16_f32 v241, v78, v79
	v_exp_f32_e32 v48, v48
	v_exp_f32_e32 v49, v49
	v_exp_f32_e32 v50, v50
	v_exp_f32_e32 v51, v51
	v_exp_f32_e32 v52, v52
	v_exp_f32_e32 v53, v53
	v_exp_f32_e32 v54, v54
	v_exp_f32_e32 v55, v55
	v_cvt_pk_bf16_f32 v242, v48, v49
	v_cvt_pk_bf16_f32 v243, v50, v51
	v_cvt_pk_bf16_f32 v244, v52, v53
	v_cvt_pk_bf16_f32 v245, v54, v55
	v_exp_f32_e32 v56, v56
	v_exp_f32_e32 v57, v57
	v_exp_f32_e32 v58, v58
	v_exp_f32_e32 v59, v59
	v_exp_f32_e32 v60, v60
	v_exp_f32_e32 v61, v61
	v_exp_f32_e32 v62, v62
	v_exp_f32_e32 v63, v63
	v_cvt_pk_bf16_f32 v246, v56, v57
	v_cvt_pk_bf16_f32 v247, v58, v59
	v_cvt_pk_bf16_f32 v248, v60, v61
	v_cvt_pk_bf16_f32 v249, v62, v63
	v_pk_add_f32 v[64:65], v[64:65], v[72:73]
	v_pk_add_f32 v[66:67], v[66:67], v[74:75]
	v_pk_add_f32 v[68:69], v[68:69], v[76:77]
	v_pk_add_f32 v[70:71], v[70:71], v[78:79]
	v_pk_add_f32 v[64:65], v[64:65], v[48:49]
	v_pk_add_f32 v[66:67], v[66:67], v[50:51]
	v_pk_add_f32 v[68:69], v[68:69], v[52:53]
	v_pk_add_f32 v[70:71], v[70:71], v[54:55]
	v_pk_add_f32 v[64:65], v[64:65], v[56:57]
	v_pk_add_f32 v[66:67], v[66:67], v[58:59]
	v_pk_add_f32 v[68:69], v[68:69], v[60:61]
	v_pk_add_f32 v[70:71], v[70:71], v[62:63]
	v_pk_add_f32 v[64:65], v[64:65], v[66:67]
	v_pk_add_f32 v[68:69], v[68:69], v[70:71]
	s_nop 0
	v_pk_add_f32 v[64:65], v[64:65], v[68:69]
	s_nop 0
	v_add_f32_e32 v172, v64, v65
	v_add_f32_e32 v157, v157, v172
	s_mov_b32 s14, 0x41000000
	s_mov_b32 s15, 0
	v_mfma_f32_32x32x16_bf16 v[16:31], v[202:205], v[234:237], v[16:31]
	v_mfma_f32_32x32x16_bf16 v[0:15], v[218:221], v[234:237], v[0:15]
	v_mfma_f32_32x32x16_bf16 v[16:31], v[206:209], v[238:241], v[16:31]
	v_mfma_f32_32x32x16_bf16 v[0:15], v[222:225], v[238:241], v[0:15]
	v_mfma_f32_32x32x16_bf16 v[16:31], v[210:213], v[242:245], v[16:31]
	v_mfma_f32_32x32x16_bf16 v[0:15], v[226:229], v[242:245], v[0:15]
	v_mfma_f32_32x32x16_bf16 v[16:31], v[214:217], v[246:249], v[16:31]
	v_mfma_f32_32x32x16_bf16 v[0:15], v[230:233], v[246:249], v[0:15]
	s_setprio 0
